# v90 with the prologue adaLN product on f32 matrix cores (v_mfma_f32_16x16x4_f32, f32 in/acc) instead of packed VALU FMAs + LDS broadcasts
# speedup vs baseline: 1.2076x; 1.2076x over previous
.LBB0_638:
	s_mul_hi_i32 s0, s5, 0x2aaaaaab
	s_lshr_b32 s1, s0, 31
	s_ashr_i32 s6, s0, 5
	s_add_i32 s6, s6, s1
	s_mul_i32 s0, s6, 0xc0
	s_sub_i32 s0, s5, s0
	s_lshl_b32 s2, s0, 5
	v_mov_b32_e32 v32, 0
	s_mul_hi_i32 s7, s6, 0x1800000
	s_mul_i32 s8, s6, 0x1800000
	s_ashr_i32 s3, s2, 31
	v_mov_b32_e32 v15, 0
	v_mov_b32_e32 v14, v32
	v_mov_b32_e32 v17, 0
	v_mov_b32_e32 v16, v32
	v_mov_b32_e32 v19, 0
	v_mov_b32_e32 v18, v32
	v_mov_b32_e32 v21, 0
	v_mov_b32_e32 v20, v32
	v_mov_b32_e32 v12, v3
	s_mov_b64 s[10:11], exec
	s_mov_b64 exec, -1
	v_readfirstlane_b32 s98, v166
	s_lshr_b32 s98, s98, 6
	v_and_b32_e32 v80, 63, v166
	v_and_b32_e32 v81, 15, v80
	v_lshrrev_b32_e32 v82, 4, v80
	s_lshl_b32 s99, s98, 7
	v_lshl_add_u32 v83, v81, 10, v82
	v_add_u32_e32 v83, s99, v83
	v_lshlrev_b32_e32 v83, 2, v83
	v_mov_b32_e32 v86, 0
	v_mov_b32_e32 v87, 0
	v_mov_b32_e32 v88, 0
	v_mov_b32_e32 v89, 0
	v_mov_b32_e32 v90, 0
	v_mov_b32_e32 v91, 0
	v_mov_b32_e32 v92, 0
	v_mov_b32_e32 v93, 0
	v_mov_b32_e32 v117, 0
	v_mov_b32_e32 v118, 0
	v_mov_b32_e32 v119, 0
	v_mov_b32_e32 v120, 0
	v_mov_b32_e32 v121, 0
	v_mov_b32_e32 v122, 0
	v_mov_b32_e32 v123, 0
	v_mov_b32_e32 v124, 0
	v_mov_b32_e32 v125, 0
	v_mov_b32_e32 v126, 0
	v_mov_b32_e32 v127, 0
	v_mov_b32_e32 v128, 0
	v_mov_b32_e32 v129, 0
	v_mov_b32_e32 v130, 0
	v_mov_b32_e32 v131, 0
	v_mov_b32_e32 v132, 0
	v_mov_b32_e32 v133, 0
	v_mov_b32_e32 v134, 0
	v_mov_b32_e32 v135, 0
	v_mov_b32_e32 v136, 0
	v_mov_b32_e32 v137, 0
	v_mov_b32_e32 v138, 0
	v_mov_b32_e32 v139, 0
	v_mov_b32_e32 v140, 0
	v_mov_b32_e32 v141, 0
	v_mov_b32_e32 v142, 0
	v_mov_b32_e32 v143, 0
	v_mov_b32_e32 v144, 0
	v_mov_b32_e32 v145, 0
	v_mov_b32_e32 v146, 0
	v_mov_b32_e32 v147, 0
	v_mov_b32_e32 v148, 0
	v_cmp_gt_u32_e64 s[0:1], 9, v81
	s_nop 1
	s_mov_b64 exec, s[0:1]
	ds_read_b32 v117, v83
	ds_read_b32 v118, v83 offset:16
	ds_read_b32 v119, v83 offset:32
	ds_read_b32 v120, v83 offset:48
	ds_read_b32 v121, v83 offset:64
	ds_read_b32 v122, v83 offset:80
	ds_read_b32 v123, v83 offset:96
	ds_read_b32 v124, v83 offset:112
	ds_read_b32 v125, v83 offset:128
	ds_read_b32 v126, v83 offset:144
	ds_read_b32 v127, v83 offset:160
	ds_read_b32 v128, v83 offset:176
	ds_read_b32 v129, v83 offset:192
	ds_read_b32 v130, v83 offset:208
	ds_read_b32 v131, v83 offset:224
	ds_read_b32 v132, v83 offset:240
	ds_read_b32 v133, v83 offset:256
	ds_read_b32 v134, v83 offset:272
	ds_read_b32 v135, v83 offset:288
	ds_read_b32 v136, v83 offset:304
	ds_read_b32 v137, v83 offset:320
	ds_read_b32 v138, v83 offset:336
	ds_read_b32 v139, v83 offset:352
	ds_read_b32 v140, v83 offset:368
	ds_read_b32 v141, v83 offset:384
	ds_read_b32 v142, v83 offset:400
	ds_read_b32 v143, v83 offset:416
	ds_read_b32 v144, v83 offset:432
	ds_read_b32 v145, v83 offset:448
	ds_read_b32 v146, v83 offset:464
	ds_read_b32 v147, v83 offset:480
	ds_read_b32 v148, v83 offset:496
	s_mov_b64 exec, -1
	s_add_u32 s0, s80, s8
	s_addc_u32 s1, s81, s7
	s_lshl_b32 s9, s2, 2
	s_add_u32 s0, s0, s9
	s_addc_u32 s1, s1, 0
	v_add_u32_e32 v84, s99, v82
	v_mul_u32_u24_e32 v84, 0x1800, v84
	v_add_u32_e32 v84, v84, v81
	v_lshlrev_b32_e32 v84, 2, v84
	global_load_dword v176, v84, s[0:1] nt
	global_load_dword v177, v84, s[0:1] offset:64 nt
	s_add_u32 s0, s0, 0x18000
	s_addc_u32 s1, s1, 0
	global_load_dword v178, v84, s[0:1] nt
	global_load_dword v179, v84, s[0:1] offset:64 nt
	s_add_u32 s0, s0, 0x18000
	s_addc_u32 s1, s1, 0
	global_load_dword v180, v84, s[0:1] nt
	global_load_dword v181, v84, s[0:1] offset:64 nt
	s_add_u32 s0, s0, 0x18000
	s_addc_u32 s1, s1, 0
	global_load_dword v182, v84, s[0:1] nt
	global_load_dword v183, v84, s[0:1] offset:64 nt
	s_add_u32 s0, s0, 0x18000
	s_addc_u32 s1, s1, 0
	global_load_dword v184, v84, s[0:1] nt
	global_load_dword v185, v84, s[0:1] offset:64 nt
	s_add_u32 s0, s0, 0x18000
	s_addc_u32 s1, s1, 0
	global_load_dword v186, v84, s[0:1] nt
	global_load_dword v187, v84, s[0:1] offset:64 nt
	s_add_u32 s0, s0, 0x18000
	s_addc_u32 s1, s1, 0
	global_load_dword v188, v84, s[0:1] nt
	global_load_dword v189, v84, s[0:1] offset:64 nt
	s_add_u32 s0, s0, 0x18000
	s_addc_u32 s1, s1, 0
	global_load_dword v190, v84, s[0:1] nt
	global_load_dword v191, v84, s[0:1] offset:64 nt
	s_add_u32 s0, s0, 0x18000
	s_addc_u32 s1, s1, 0
	global_load_dword v192, v84, s[0:1] nt
	global_load_dword v193, v84, s[0:1] offset:64 nt
	s_add_u32 s0, s0, 0x18000
	s_addc_u32 s1, s1, 0
	global_load_dword v194, v84, s[0:1] nt
	global_load_dword v195, v84, s[0:1] offset:64 nt
	s_add_u32 s0, s0, 0x18000
	s_addc_u32 s1, s1, 0
	global_load_dword v196, v84, s[0:1] nt
	global_load_dword v197, v84, s[0:1] offset:64 nt
	s_add_u32 s0, s0, 0x18000
	s_addc_u32 s1, s1, 0
	global_load_dword v198, v84, s[0:1] nt
	global_load_dword v199, v84, s[0:1] offset:64 nt
	s_add_u32 s0, s0, 0x18000
	s_addc_u32 s1, s1, 0
	global_load_dword v200, v84, s[0:1] nt
	global_load_dword v201, v84, s[0:1] offset:64 nt
	s_add_u32 s0, s0, 0x18000
	s_addc_u32 s1, s1, 0
	global_load_dword v202, v84, s[0:1] nt
	global_load_dword v203, v84, s[0:1] offset:64 nt
	s_add_u32 s0, s0, 0x18000
	s_addc_u32 s1, s1, 0
	global_load_dword v204, v84, s[0:1] nt
	global_load_dword v205, v84, s[0:1] offset:64 nt
	s_add_u32 s0, s0, 0x18000
	s_addc_u32 s1, s1, 0
	global_load_dword v206, v84, s[0:1] nt
	global_load_dword v207, v84, s[0:1] offset:64 nt
	s_add_u32 s0, s0, 0x18000
	s_addc_u32 s1, s1, 0
	s_waitcnt lgkmcnt(0)
	s_waitcnt vmcnt(30)
	v_mfma_f32_16x16x4_f32 v[86:89], v117, v176, v[86:89]
	v_mfma_f32_16x16x4_f32 v[90:93], v117, v177, v[90:93]
	global_load_dword v208, v84, s[0:1] nt
	global_load_dword v209, v84, s[0:1] offset:64 nt
	s_add_u32 s0, s0, 0x18000
	s_addc_u32 s1, s1, 0
	s_waitcnt vmcnt(30)
	v_mfma_f32_16x16x4_f32 v[86:89], v118, v178, v[86:89]
	v_mfma_f32_16x16x4_f32 v[90:93], v118, v179, v[90:93]
	global_load_dword v210, v84, s[0:1] nt
	global_load_dword v211, v84, s[0:1] offset:64 nt
	s_add_u32 s0, s0, 0x18000
	s_addc_u32 s1, s1, 0
	s_waitcnt vmcnt(30)
	v_mfma_f32_16x16x4_f32 v[86:89], v119, v180, v[86:89]
	v_mfma_f32_16x16x4_f32 v[90:93], v119, v181, v[90:93]
	global_load_dword v212, v84, s[0:1] nt
	global_load_dword v213, v84, s[0:1] offset:64 nt
	s_add_u32 s0, s0, 0x18000
	s_addc_u32 s1, s1, 0
	s_waitcnt vmcnt(30)
	v_mfma_f32_16x16x4_f32 v[86:89], v120, v182, v[86:89]
	v_mfma_f32_16x16x4_f32 v[90:93], v120, v183, v[90:93]
	global_load_dword v233, v84, s[0:1] nt
	global_load_dword v234, v84, s[0:1] offset:64 nt
	s_add_u32 s0, s0, 0x18000
	s_addc_u32 s1, s1, 0
	s_waitcnt vmcnt(30)
	v_mfma_f32_16x16x4_f32 v[86:89], v121, v184, v[86:89]
	v_mfma_f32_16x16x4_f32 v[90:93], v121, v185, v[90:93]
	global_load_dword v235, v84, s[0:1] nt
	global_load_dword v236, v84, s[0:1] offset:64 nt
	s_add_u32 s0, s0, 0x18000
	s_addc_u32 s1, s1, 0
	s_waitcnt vmcnt(30)
	v_mfma_f32_16x16x4_f32 v[86:89], v122, v186, v[86:89]
	v_mfma_f32_16x16x4_f32 v[90:93], v122, v187, v[90:93]
	global_load_dword v237, v84, s[0:1] nt
	global_load_dword v238, v84, s[0:1] offset:64 nt
	s_add_u32 s0, s0, 0x18000
	s_addc_u32 s1, s1, 0
	s_waitcnt vmcnt(30)
	v_mfma_f32_16x16x4_f32 v[86:89], v123, v188, v[86:89]
	v_mfma_f32_16x16x4_f32 v[90:93], v123, v189, v[90:93]
	global_load_dword v239, v84, s[0:1] nt
	global_load_dword v240, v84, s[0:1] offset:64 nt
	s_add_u32 s0, s0, 0x18000
	s_addc_u32 s1, s1, 0
	s_waitcnt vmcnt(30)
	v_mfma_f32_16x16x4_f32 v[86:89], v124, v190, v[86:89]
	v_mfma_f32_16x16x4_f32 v[90:93], v124, v191, v[90:93]
	global_load_dword v241, v84, s[0:1] nt
	global_load_dword v242, v84, s[0:1] offset:64 nt
	s_add_u32 s0, s0, 0x18000
	s_addc_u32 s1, s1, 0
	s_waitcnt vmcnt(30)
	v_mfma_f32_16x16x4_f32 v[86:89], v125, v192, v[86:89]
	v_mfma_f32_16x16x4_f32 v[90:93], v125, v193, v[90:93]
	global_load_dword v243, v84, s[0:1] nt
	global_load_dword v244, v84, s[0:1] offset:64 nt
	s_add_u32 s0, s0, 0x18000
	s_addc_u32 s1, s1, 0
	s_waitcnt vmcnt(30)
	v_mfma_f32_16x16x4_f32 v[86:89], v126, v194, v[86:89]
	v_mfma_f32_16x16x4_f32 v[90:93], v126, v195, v[90:93]
	global_load_dword v245, v84, s[0:1] nt
	global_load_dword v246, v84, s[0:1] offset:64 nt
	s_add_u32 s0, s0, 0x18000
	s_addc_u32 s1, s1, 0
	s_waitcnt vmcnt(30)
	v_mfma_f32_16x16x4_f32 v[86:89], v127, v196, v[86:89]
	v_mfma_f32_16x16x4_f32 v[90:93], v127, v197, v[90:93]
	global_load_dword v247, v84, s[0:1] nt
	global_load_dword v248, v84, s[0:1] offset:64 nt
	s_add_u32 s0, s0, 0x18000
	s_addc_u32 s1, s1, 0
	s_waitcnt vmcnt(30)
	v_mfma_f32_16x16x4_f32 v[86:89], v128, v198, v[86:89]
	v_mfma_f32_16x16x4_f32 v[90:93], v128, v199, v[90:93]
	global_load_dword v249, v84, s[0:1] nt
	global_load_dword v102, v84, s[0:1] offset:64 nt
	s_add_u32 s0, s0, 0x18000
	s_addc_u32 s1, s1, 0
	s_waitcnt vmcnt(30)
	v_mfma_f32_16x16x4_f32 v[86:89], v129, v200, v[86:89]
	v_mfma_f32_16x16x4_f32 v[90:93], v129, v201, v[90:93]
	global_load_dword v103, v84, s[0:1] nt
	global_load_dword v104, v84, s[0:1] offset:64 nt
	s_add_u32 s0, s0, 0x18000
	s_addc_u32 s1, s1, 0
	s_waitcnt vmcnt(30)
	v_mfma_f32_16x16x4_f32 v[86:89], v130, v202, v[86:89]
	v_mfma_f32_16x16x4_f32 v[90:93], v130, v203, v[90:93]
	global_load_dword v105, v84, s[0:1] nt
	global_load_dword v106, v84, s[0:1] offset:64 nt
	s_add_u32 s0, s0, 0x18000
	s_addc_u32 s1, s1, 0
	s_waitcnt vmcnt(30)
	v_mfma_f32_16x16x4_f32 v[86:89], v131, v204, v[86:89]
	v_mfma_f32_16x16x4_f32 v[90:93], v131, v205, v[90:93]
	global_load_dword v107, v84, s[0:1] nt
	global_load_dword v108, v84, s[0:1] offset:64 nt
	s_add_u32 s0, s0, 0x18000
	s_addc_u32 s1, s1, 0
	s_waitcnt vmcnt(30)
	v_mfma_f32_16x16x4_f32 v[86:89], v132, v206, v[86:89]
	v_mfma_f32_16x16x4_f32 v[90:93], v132, v207, v[90:93]
	global_load_dword v109, v84, s[0:1] nt
	global_load_dword v110, v84, s[0:1] offset:64 nt
	s_add_u32 s0, s0, 0x18000
	s_addc_u32 s1, s1, 0
	s_waitcnt vmcnt(30)
	v_mfma_f32_16x16x4_f32 v[86:89], v133, v208, v[86:89]
	v_mfma_f32_16x16x4_f32 v[90:93], v133, v209, v[90:93]
	s_waitcnt vmcnt(28)
	v_mfma_f32_16x16x4_f32 v[86:89], v134, v210, v[86:89]
	v_mfma_f32_16x16x4_f32 v[90:93], v134, v211, v[90:93]
	s_waitcnt vmcnt(26)
	v_mfma_f32_16x16x4_f32 v[86:89], v135, v212, v[86:89]
	v_mfma_f32_16x16x4_f32 v[90:93], v135, v213, v[90:93]
	s_waitcnt vmcnt(24)
	v_mfma_f32_16x16x4_f32 v[86:89], v136, v233, v[86:89]
	v_mfma_f32_16x16x4_f32 v[90:93], v136, v234, v[90:93]
	s_waitcnt vmcnt(22)
	v_mfma_f32_16x16x4_f32 v[86:89], v137, v235, v[86:89]
	v_mfma_f32_16x16x4_f32 v[90:93], v137, v236, v[90:93]
	s_waitcnt vmcnt(20)
	v_mfma_f32_16x16x4_f32 v[86:89], v138, v237, v[86:89]
	v_mfma_f32_16x16x4_f32 v[90:93], v138, v238, v[90:93]
	s_waitcnt vmcnt(18)
	v_mfma_f32_16x16x4_f32 v[86:89], v139, v239, v[86:89]
	v_mfma_f32_16x16x4_f32 v[90:93], v139, v240, v[90:93]
	s_waitcnt vmcnt(16)
	v_mfma_f32_16x16x4_f32 v[86:89], v140, v241, v[86:89]
	v_mfma_f32_16x16x4_f32 v[90:93], v140, v242, v[90:93]
	s_waitcnt vmcnt(14)
	v_mfma_f32_16x16x4_f32 v[86:89], v141, v243, v[86:89]
	v_mfma_f32_16x16x4_f32 v[90:93], v141, v244, v[90:93]
	s_waitcnt vmcnt(12)
	v_mfma_f32_16x16x4_f32 v[86:89], v142, v245, v[86:89]
	v_mfma_f32_16x16x4_f32 v[90:93], v142, v246, v[90:93]
	s_waitcnt vmcnt(10)
	v_mfma_f32_16x16x4_f32 v[86:89], v143, v247, v[86:89]
	v_mfma_f32_16x16x4_f32 v[90:93], v143, v248, v[90:93]
	s_waitcnt vmcnt(8)
	v_mfma_f32_16x16x4_f32 v[86:89], v144, v249, v[86:89]
	v_mfma_f32_16x16x4_f32 v[90:93], v144, v102, v[90:93]
	s_waitcnt vmcnt(6)
	v_mfma_f32_16x16x4_f32 v[86:89], v145, v103, v[86:89]
	v_mfma_f32_16x16x4_f32 v[90:93], v145, v104, v[90:93]
	s_waitcnt vmcnt(4)
	v_mfma_f32_16x16x4_f32 v[86:89], v146, v105, v[86:89]
	v_mfma_f32_16x16x4_f32 v[90:93], v146, v106, v[90:93]
	s_waitcnt vmcnt(2)
	v_mfma_f32_16x16x4_f32 v[86:89], v147, v107, v[86:89]
	v_mfma_f32_16x16x4_f32 v[90:93], v147, v108, v[90:93]
	s_waitcnt vmcnt(0)
	v_mfma_f32_16x16x4_f32 v[86:89], v148, v109, v[86:89]
	v_mfma_f32_16x16x4_f32 v[90:93], v148, v110, v[90:93]
	s_mov_b64 exec, s[10:11]
	s_barrier
	s_mov_b64 s[10:11], exec
	s_mov_b64 exec, -1
	s_lshl_b32 s9, s98, 11
	s_add_i32 s9, s9, 0x15900
	v_lshlrev_b32_e32 v85, 9, v82
	v_lshl_add_u32 v85, v81, 2, v85
	v_add_u32_e32 v85, s9, v85
	v_lshl_add_u32 v83, v80, 2, s9
	s_nop 7
	s_nop 7
	ds_write_b32 v85, v86 offset:0
	ds_write_b32 v85, v90 offset:64
	ds_write_b32 v85, v87 offset:128
	ds_write_b32 v85, v91 offset:192
	ds_write_b32 v85, v88 offset:256
	ds_write_b32 v85, v92 offset:320
	ds_write_b32 v85, v89 offset:384
	ds_write_b32 v85, v93 offset:448
	v_mov_b32_e32 v20, 0
	v_mov_b32_e32 v21, 0
	v_mov_b32_e32 v18, 0
	v_mov_b32_e32 v19, 0
	v_mov_b32_e32 v16, 0
	v_mov_b32_e32 v17, 0
	v_mov_b32_e32 v14, 0
	v_mov_b32_e32 v15, 0
	v_mov_b32_e32 v32, 0
	s_waitcnt lgkmcnt(0)
	s_mov_b32 exec_lo, -1
	s_mov_b32 exec_hi, 0
	ds_read_b32 v20, v83
	ds_read_b32 v21, v83 offset:128
	ds_read_b32 v18, v83 offset:256
	ds_read_b32 v19, v83 offset:384
	ds_read_b32 v16, v83 offset:512
	ds_read_b32 v17, v83 offset:640
	ds_read_b32 v14, v83 offset:768
	ds_read_b32 v15, v83 offset:896
	ds_read_b32 v32, v83 offset:1024
	s_waitcnt lgkmcnt(0)
	s_mov_b64 exec, s[10:11]
	ds_write2st64_b32 v31, v20, v21 offset1:1
	ds_write2st64_b32 v31, v18, v19 offset0:2 offset1:3
	ds_write2st64_b32 v31, v16, v17 offset0:4 offset1:5
	ds_write2st64_b32 v31, v14, v15 offset0:6 offset1:7
	ds_write_b32 v31, v32 offset:2048
	s_waitcnt lgkmcnt(0)
	s_barrier
	s_and_saveexec_b64 s[22:23], vcc
	s_cbranch_execz .LBB0_637
	s_mul_i32 s0, s6, 0x1800
	s_add_i32 s0, s0, s2
	v_or_b32_e32 v10, s0, v2
	v_ashrrev_i32_e32 v11, 31, v10
	s_mul_i32 s6, s6, 9
	v_lshl_add_u64 v[10:11], v[10:11], 2, s[82:83]
	v_lshl_add_u64 v[12:13], s[2:3], 2, v[4:5]
	s_mov_b64 s[2:3], 0
	v_mov_b32_e32 v0, v166
